# grid barrier tail rewritten: XCD leaders add to one top counter, every workgroup polls it against (gen+1)*nxcd; early L1 invalidate
# baseline (speedup 1.0000x reference)
; __device__ __forceinline__ unsigned xb_ld(unsigned* p) { return __hip_atomic_load(p, __ATOMIC_RELAXED, __HIP_MEMORY_SCOPE_AGENT); }
; __device__ __forceinline__ unsigned xb_add(unsigned* p, unsigned v) { return __hip_atomic_fetch_add(p, v, __ATOMIC_RELAXED, __HIP_MEMORY_SCOPE_AGENT); }
; #define XB_SPIN(cond, bar) do { unsigned _sp = 0; while (cond) { __builtin_amdgcn_s_sleep(0); \
;     if ((++_sp & 255u) == 0u) { if (xb_ld(&(bar)[XB_TMO])) break; if (_sp > XB_SPIN_CAP) { atomicAdd(&(bar)[XB_TMO], 1u); break; } } } } while (0)
; __device__ __forceinline__ void xcd_barrier(XcdBarrier& b, const int tid, const unsigned G) {
;     ...
;     const unsigned nloc = b.nloc, nx = b.nx;
;     const unsigned old = xb_add(&bar[XB_XSUB(b.x)], 1u);
;     const unsigned gen = old / nloc;
;     if (old + 1u == (gen + 1u) * nloc) {
;       __builtin_amdgcn_fence(__ATOMIC_RELEASE, "agent");
;       asm volatile("s_waitcnt vmcnt(0)" ::: "memory");
;       const unsigned og = xb_add(&bar[XB_TOP], 1u);
;       const unsigned tg = og / nx;
;       if (og + 1u == (tg + 1u) * nx) xb_add(&bar[XB_TOPGEN], 1u);
;       else XB_SPIN(xb_ld(&bar[XB_TOPGEN]) == tg, bar);
;       __builtin_amdgcn_fence(__ATOMIC_ACQUIRE, "agent");
;       xb_add(&bar[XB_XGEN(b.x)], 1u);
;       asm volatile("s_waitcnt vmcnt(0)" ::: "memory");
;     } else {
;       XB_SPIN(xb_ld(&bar[XB_XGEN(b.x)]) == gen, bar);
;       __builtin_amdgcn_fence(__ATOMIC_ACQUIRE, "agent");
;       asm volatile("s_waitcnt vmcnt(0)" ::: "memory");
.LBB0_50:
	s_or_b64 exec, exec, s[34:35]
	s_waitcnt vmcnt(0)
	v_readfirstlane_b32 s23, v1
	v_sub_u32_e32 v2, 0, v126
	s_nop 0
	v_add_u32_e32 v1, s23, v0
	v_cvt_f32_u32_e32 v0, v126
	v_rcp_iflag_f32_e32 v0, v0
	s_nop 0
	v_mul_f32_e32 v0, 0x4f7ffffe, v0
	v_cvt_u32_f32_e32 v0, v0
	v_mul_lo_u32 v2, v2, v0
	v_mul_hi_u32 v2, v0, v2
	v_add_u32_e32 v0, v0, v2
	v_mul_hi_u32 v0, v1, v0
	v_mul_lo_u32 v2, v0, v126
	v_sub_u32_e32 v2, v1, v2
	v_cmp_ge_u32_e32 vcc, v2, v126
	v_add_u32_e32 v4, 1, v0
	v_add_u32_e32 v1, 1, v1
	v_cndmask_b32_e32 v0, v0, v4, vcc
	v_sub_u32_e32 v4, v2, v126
	v_cndmask_b32_e32 v2, v2, v4, vcc
	v_cmp_ge_u32_e32 vcc, v2, v126
	v_add_u32_e32 v2, 1, v0
	s_nop 0
	v_cndmask_b32_e32 v0, v0, v2, vcc
	v_mad_u64_u32 v[4:5], s[24:25], v126, v0, v[126:127]
	v_cmp_ne_u32_e32 vcc, v1, v4
	v_add_u32_e32 v2, 1, v0
	v_mul_lo_u32 v2, v2, v128
	v_readlane_b32 s24, v253, 13
	v_readlane_b32 s25, v253, 14
	s_nop 4
	s_cbranch_vccnz .Lxb_wait
	buffer_wbl2 sc1
	s_waitcnt vmcnt(0)
	global_atomic_add v3, v129, s[24:25]

; __device__ __forceinline__ unsigned xb_ld(unsigned* p) { return __hip_atomic_load(p, __ATOMIC_RELAXED, __HIP_MEMORY_SCOPE_AGENT); }
; __device__ __forceinline__ unsigned xb_add(unsigned* p, unsigned v) { return __hip_atomic_fetch_add(p, v, __ATOMIC_RELAXED, __HIP_MEMORY_SCOPE_AGENT); }
; #define XB_SPIN(cond, bar) do { unsigned _sp = 0; while (cond) { __builtin_amdgcn_s_sleep(0); \
;     if ((++_sp & 255u) == 0u) { if (xb_ld(&(bar)[XB_TMO])) break; if (_sp > XB_SPIN_CAP) { atomicAdd(&(bar)[XB_TMO], 1u); break; } } } } while (0)
; __device__ __forceinline__ void xcd_barrier(XcdBarrier& b, const int tid, const unsigned G) {
;     ...
;       const unsigned og = xb_add(&bar[XB_TOP], 1u);
;       const unsigned tg = og / nx;
;       if (og + 1u == (tg + 1u) * nx) xb_add(&bar[XB_TOPGEN], 1u);
;       else XB_SPIN(xb_ld(&bar[XB_TOPGEN]) == tg, bar);
;       __builtin_amdgcn_fence(__ATOMIC_ACQUIRE, "agent");
;       xb_add(&bar[XB_XGEN(b.x)], 1u);
;       asm volatile("s_waitcnt vmcnt(0)" ::: "memory");
;     } else {
;       XB_SPIN(xb_ld(&bar[XB_XGEN(b.x)]) == gen, bar);
;       __builtin_amdgcn_fence(__ATOMIC_ACQUIRE, "agent");
;       asm volatile("s_waitcnt vmcnt(0)" ::: "memory");
.Lxb_spin:
	global_load_dword v1, v3, s[24:25] sc1
	s_waitcnt vmcnt(0)
	v_cmp_lt_u32_e32 vcc, v1, v2
	s_cbranch_vccz .Lxb_done
	s_sleep 0
	s_branch .Lxb_spin
.Lxb_done:
.LBB0_84:
	s_or_b64 exec, exec, s[34:35]
